# P0 row loop: one static s_setprio 1 for waves 4-7 (reset after the loop)
# speedup vs baseline: 1.0027x; 1.0020x over previous
.LBB0_19:
	s_or_b64 exec, exec, s[6:7]
	s_lshl_b32 s4, s87, 3
	s_ashr_i32 s3, s3, 6
	s_add_i32 s18, s3, s4
	s_lshl_b32 s20, s92, 3
	v_and_b32_e32 v45, 63, v44
	s_cmpk_lt_i32 s18, 0x4000
	s_waitcnt lgkmcnt(0)
	s_barrier
	s_cbranch_scc0 .LBB0_28
	s_add_u32 s24, s72, 0x300000
	s_addc_u32 s25, s73, 0
	s_ashr_i32 s19, s18, 31
	s_lshl_b64 s[4:5], s[18:19], 12
	s_add_u32 s4, s52, s4
	s_addc_u32 s5, s53, s5
	v_lshlrev_b32_e32 v34, 4, v45
	global_load_dwordx4 v[30:33], v34, s[4:5]
	global_load_dwordx4 v[26:29], v34, s[4:5] offset:1024
	global_load_dwordx4 v[22:25], v34, s[4:5] offset:2048
	global_load_dwordx4 v[18:21], v34, s[4:5] offset:3072
	v_mbcnt_lo_u32_b32 v1, -1, 0
	v_mbcnt_hi_u32_b32 v2, -1, v1
	v_and_b32_e32 v1, 64, v2
	v_add_u32_e32 v3, 64, v1
	v_xor_b32_e32 v1, 1, v2
	v_cmp_lt_i32_e32 vcc, v1, v3
	v_xor_b32_e32 v4, 2, v2
	s_lshl_b64 s[4:5], s[18:19], 11
	v_cndmask_b32_e32 v1, v2, v1, vcc
	v_cmp_lt_i32_e32 vcc, v4, v3
	s_ashr_i32 s21, s20, 31
	v_mov_b32_e32 v35, 0
	v_cndmask_b32_e32 v4, v2, v4, vcc
	v_lshlrev_b32_e32 v46, 2, v4
	v_xor_b32_e32 v4, 4, v2
	v_cmp_lt_i32_e32 vcc, v4, v3
	v_bfe_u32 v52, v44, 2, 4
	v_lshl_or_b32 v40, v45, 3, s4
	v_cndmask_b32_e32 v4, v2, v4, vcc
	v_lshlrev_b32_e32 v47, 2, v4
	v_xor_b32_e32 v4, 8, v2
	v_cmp_lt_i32_e32 vcc, v4, v3
	v_mov_b32_e32 v41, s5
	s_lshl_b64 s[28:29], s[20:21], 11
	v_cndmask_b32_e32 v4, v2, v4, vcc
	v_lshlrev_b32_e32 v48, 2, v4
	v_xor_b32_e32 v4, 16, v2
	v_cmp_lt_i32_e32 vcc, v4, v3
	s_lshl_b64 s[4:5], s[18:19], 2
	v_lshl_add_u64 v[36:37], s[52:53], 0, v[34:35]
	v_cndmask_b32_e32 v4, v2, v4, vcc
	v_lshlrev_b32_e32 v49, 2, v4
	v_xor_b32_e32 v4, 32, v2
	v_cmp_lt_i32_e32 vcc, v4, v3
	v_add_u32_e32 v51, 0, v34
	v_lshlrev_b32_e32 v34, 2, v52
	v_cndmask_b32_e32 v2, v2, v4, vcc
	v_lshlrev_b32_e32 v50, 2, v2
	v_and_b32_e32 v2, 32, v44
	v_cmp_eq_u32_e64 s[8:9], 0, v2
	v_and_b32_e32 v2, 16, v44
	v_cmp_eq_u32_e64 s[10:11], 0, v2
	v_and_b32_e32 v2, 8, v44
	v_cmp_eq_u32_e64 s[12:13], 0, v2
	v_and_b32_e32 v2, 4, v44
	v_cmp_eq_u32_e64 s[14:15], 0, v2
	v_and_b32_e32 v2, 3, v44
	v_cmp_eq_u32_e64 s[16:17], 0, v2
	s_add_u32 s4, s4, 0x10000
	s_mov_b32 s27, 0
	v_lshlrev_b32_e32 v1, 2, v1
	v_cmp_eq_u32_e64 s[6:7], 0, v45
	v_lshl_add_u64 v[38:39], s[60:61], 0, v[34:35]
	s_addc_u32 s5, s5, 0
	s_lshl_b64 s[30:31], s[20:21], 2
	s_movk_i32 s19, 0x7fff
	s_mov_b32 s21, 0xffff0000
	s_mov_b32 s33, 0x3800000
	v_mov_b32_e32 v34, 0x358637bd
	s_mov_b32 s74, 0x800000
	s_mov_b32 s75, 0xbfb8aa3b
	s_mov_b32 s76, 0xb2a5705f
	s_mov_b32 s77, 0x42ce8ed0
	s_mov_b32 s80, 0xc2b17218
	s_mov_b32 s81, 0x7f800000
	s_mov_b32 s82, 0x3f2aaaab
	v_mov_b32_e32 v53, 0x3ecc95a3
	s_mov_b32 s83, 0x3f317218
	s_mov_b32 s85, 0x33800000
	v_mov_b32_e32 v54, 0x7f800000
	v_mov_b32_e32 v42, 0x3f317218
	s_mov_b32 s26, s18
	v_mov_b32_e32 v2, 0
	v_mov_b32_e32 v3, v35
	v_mov_b32_e32 v4, v35
	v_mov_b32_e32 v5, v35
	v_mov_b32_e32 v6, 0
	v_mov_b32_e32 v7, v35
	v_mov_b32_e32 v8, v35
	v_mov_b32_e32 v9, v35
	v_mov_b32_e32 v10, 0
	v_mov_b32_e32 v11, v35
	v_mov_b32_e32 v12, v35
	v_mov_b32_e32 v13, v35
	v_mov_b32_e32 v14, 0
	v_mov_b32_e32 v15, v35
	v_mov_b32_e32 v16, v35
	v_mov_b32_e32 v17, v35
	v_readfirstlane_b32 s98, v182
	s_lshr_b32 s98, s98, 8
	s_cmp_lg_u32 s98, 0
	s_cbranch_scc0 .Lp0_prio_skip
	s_setprio 1
.Lp0_prio_skip:
	s_branch .LBB0_22
.LBB0_21:
	s_or_b64 exec, exec, s[60:61]
	s_add_u32 s4, s4, s30
	v_lshl_add_u64 v[40:41], v[40:41], 0, s[28:29]
	s_addc_u32 s5, s5, s31
	s_andn2_b64 vcc, exec, s[52:53]
	s_mov_b32 s26, s34
	s_waitcnt vmcnt(4)
	v_mov_b32_e32 v30, v2
	v_mov_b32_e32 v31, v3
	v_mov_b32_e32 v32, v4
	v_mov_b32_e32 v33, v5
	v_mov_b32_e32 v26, v6
	v_mov_b32_e32 v27, v7
	v_mov_b32_e32 v28, v8
	v_mov_b32_e32 v29, v9
	v_mov_b32_e32 v22, v10
	v_mov_b32_e32 v23, v11
	v_mov_b32_e32 v24, v12
	v_mov_b32_e32 v25, v13
	v_mov_b32_e32 v18, v14
	s_waitcnt lgkmcnt(0)
	v_mov_b32_e32 v19, v15
	v_mov_b32_e32 v20, v16
	v_mov_b32_e32 v21, v17
	s_cbranch_vccz .LBB0_28

.LBB0_28:
	s_setprio 0
	v_lshl_add_u32 v4, s2, 9, v44
	s_mov_b32 s4, 0x40000
	v_cmp_gt_i32_e32 vcc, s4, v4
	v_and_b32_e32 v1, 31, v44
	s_and_saveexec_b64 s[6:7], vcc
	s_cbranch_execz .LBB0_31
	v_cvt_f32_ubyte0_e32 v2, v1
	v_mul_f32_e32 v3, 0xbed49a78, v2
	s_mov_b32 s4, 0xc2fc0000
	v_mov_b32_e32 v5, 0x42800000
	v_cmp_gt_f32_e32 vcc, s4, v3
	s_add_u32 s8, s72, 0x100000
	s_mov_b32 s12, 0x6dc9c883
	v_cndmask_b32_e32 v3, 0, v5, vcc
	v_fmac_f32_e32 v3, 0xbed49a78, v2
	v_exp_f32_e32 v2, v3
	v_not_b32_e32 v3, 63
	v_cndmask_b32_e32 v3, 0, v3, vcc
	s_addc_u32 s9, s73, 0
	v_ldexp_f32 v5, v2, v3
	v_lshlrev_b32_e32 v2, 1, v44
	s_lshl_b32 s4, s92, 9
	v_lshl_add_u32 v2, s2, 10, v2
	s_lshl_b32 s5, s92, 10
	s_mov_b64 s[10:11], 0
	s_mov_b32 s13, 0x3fc45f30
	s_mov_b32 s14, 0x3ffff
